# E10 + static s_setprio 1 for waves 4-7 during the dense-attention (mixer C) part, reset at the start of the A/B/D part
# speedup vs baseline: 1.0003x; 1.0003x over previous
; #define WAIT_BAR(N) asm volatile("s_waitcnt vmcnt(" #N ") lgkmcnt(0)\n\ts_barrier" ::: "memory")
;   #define DMA_K(t, slot) glds16(ksrc + (long)(t) * KVBLK * PQ, (unsigned)__builtin_amdgcn_readfirstlane(kdst + (slot)))
; template <int THRL> __device__ __forceinline__ void attn_unit(const int tid, const float mfix, int q0, int NT, const bf16* Qh, const bf16* __restrict__ Kh, const bf16* __restrict__ Vh, const bf16* Zh, bf16* Oh, const long PQ, const long PO, char* shm) {
;   const int lane = tid & 63, r32 = lane & 31, hi = lane >> 5; const int wid = __builtin_amdgcn_readfirstlane(tid >> 6);
;   const bf16* Qw = Qh + (long)(q0 + wid * QBLK) * PQ;
;   const unsigned lds0 = (unsigned)(uintptr_t)shm;
;   float* wsf = (float*)(shm + LDS_WS) + wid * 64;
;   const bf16* ksrc = Kh + (long)lane * PQ + wid * 8;
;   const bf16* vsrc = Vh + (long)(16 * (wid & 3) + (lane >> 2)) * PQ + (wid >> 2) * 32 + (lane & 3) * 8;
;   const unsigned kdst = lds0 + LDS_K + wid * 1024, vdst = lds0 + LDS_V + wid * 1024;
;     ...
;   const int vb0 = (int)(lds0 + LDS_V) + ((lane >> 4) & 1) * 32 + (lane & 3) * 8 + (4 * hi + ((lane & 15) >> 2)) * 64;
;   const char* Kbase = shm + LDS_K; bf16x8 kf[8];
;   const lds_cptr shm3 = (lds_cptr)shm; const lds_cptr kp0 = shm3 + LDS_K + hi * 1024 + r32 * 16; const lds_cptr vp0 = shm3 + LDS_V + ((lane >> 4) & 1) * 32 + (lane & 3) * 8 + (4 * hi + ((lane & 15) >> 2)) * 64;
;   DMA_K(0, 0); DMA_V(0, 0); DMA_K(1, SLOTB);
;   bf16x8 qr[4];
;   #pragma unroll
;   for (int d0 = 0; d0 < 4; ++d0) qr[d0] = *reinterpret_cast<const bf16x8*>(&Qw[(long)r32 * PQ + d0 * 16 + hi * 8]);
;   float zf_; asm volatile("v_mov_b32 %0, 0" : "=v"(zf_)); f32x16 zv_;
;   #pragma unroll
;   for (int r = 0; r < 16; ++r) zv_[r] = zf_;
;   float l_reg = 0.f; f32x16 o[2]; o[0] = zv_; o[1] = zv_; f32x16 negm;
;   #pragma unroll
;   for (int r = 0; r < 16; ++r) negm[r] = -mfix;
;   asm volatile("" : "+v"(negm));
;     ...
;   f32x16 pA0, pA1, pB0, pB1;
;   int sl_prev = 0, sl_cur = 0, sl_next = SLOTB;
;     ...
;   DMA_K(2, 2 * SLOTB);
;   WAIT_BAR(3);
;   qkt(pA0, pA1, Kbase, qr, negm, r32, hi); asm volatile("s_nop 15\n\ts_nop 7" : "+v"(pA0), "+v"(pA1));
;   START(pA0, pA1);
;   _Pragma("unroll") for (int r = 0; r < 16; ++r) pA1[r] = __builtin_amdgcn_exp2f(pA1[r]);
;   WAIT_BAR(0);
;   DMA_K(3, 0); DMA_V(1, SLOTB);
;   ROT();
;   kload8(kf, kp0 + sl_cur);
;   WAIT_BAR(2);
.LBB0_387:
	s_or_b32 s1, s1, s0
	v_readfirstlane_b32 s20, v238
	s_xor_b64 s[8:9], s[10:11], -1
	s_lshl_b32 s10, s1, 8
	s_ashr_i32 s1, s20, 6
	s_cmp_lt_u32 s1, 4
	s_cbranch_scc1 .Lattn_prio_skip
	s_setprio 1
.Lattn_prio_skip:
	s_nop 0
	s_lshl_b32 s16, s1, 4
	v_and_or_b32 v16, s16, 48, v240
	s_ashr_i32 s16, s20, 3
	s_lshl_b32 s11, s1, 5
	s_lshl_b32 s14, s1, 3
	s_andn2_b32 s16, s16, 31
	s_add_i32 s10, s11, s10
	s_ashr_i32 s15, s14, 31
	s_ashr_i32 s17, s16, 31
	s_ashr_i32 s11, s10, 31
	s_lshl_b64 s[14:15], s[14:15], 1
	v_mul_u32_u24_e32 v16, 0x1a40, v16
	s_lshl_b64 s[16:17], s[16:17], 1
	s_lshl_b32 s19, s1, 10
	v_lshlrev_b32_e32 v188, 1, v16
	s_cmp_lg_u32 0, -1
	v_lshl_add_u64 v[16:17], s[6:7], 0, v[188:189]
	s_cselect_b32 s18, 0, 0
	v_lshl_add_u64 v[222:223], v[190:191], 0, s[14:15]
	v_lshl_add_u64 v[16:17], v[16:17], 0, s[16:17]
	v_mov_b32_e32 v219, v189
	s_add_i32 s19, s19, s18
	s_mov_b32 s21, m0
	s_mov_b32 m0, s19
	s_nop 0
	global_load_lds_dwordx4 v[222:223], off
	s_mov_b32 m0, s21
	s_mul_hi_i32 s13, s10, 0x1a40
	s_mul_i32 s12, s10, 0x1a40
	v_lshl_add_u64 v[220:221], v[16:17], 0, v[218:219]
	s_add_i32 s18, s19, 0x6000
	s_mov_b32 s21, m0
	s_mov_b32 m0, s18
	s_nop 0
	global_load_lds_dwordx4 v[220:221], off
	s_mov_b32 m0, s21
	v_lshl_add_u64 v[16:17], v[222:223], 0, s[86:87]
	s_add_i32 s21, s19, 0x2000
	s_mov_b32 s22, m0
	s_mov_b32 m0, s21
	s_nop 0
	global_load_lds_dwordx4 v[16:17], off
	s_mov_b32 m0, s22
	v_lshl_add_u64 v[16:17], s[12:13], 1, v[192:193]
	global_load_dwordx4 v[172:175], v[16:17], off
	global_load_dwordx4 v[168:171], v[16:17], off offset:32
	global_load_dwordx4 v[164:167], v[16:17], off offset:64
	global_load_dwordx4 v[152:155], v[16:17], off offset:96
	v_mov_b64_e32 v[62:63], v[14:15]
	v_mov_b64_e32 v[60:61], v[12:13]
	v_mov_b64_e32 v[58:59], v[10:11]
	v_mov_b64_e32 v[56:57], v[8:9]
	v_mov_b64_e32 v[54:55], v[6:7]
	v_mov_b64_e32 v[52:53], v[4:5]
	v_mov_b64_e32 v[50:51], v[2:3]
	v_mov_b64_e32 v[48:49], v[0:1]
	v_lshl_add_u64 v[18:19], v[222:223], 0, s[88:89]
	s_add_i32 s21, s19, 0x4000
	v_mov_b32 v16, 0
	s_mov_b32 s22, m0
	s_mov_b32 m0, s21
	s_nop 0
	global_load_lds_dwordx4 v[18:19], off
	s_mov_b32 m0, s22
	s_waitcnt vmcnt(3) lgkmcnt(0)
	s_barrier
	ds_read_b128 v[18:21], v242
	ds_read_b128 v[40:43], v242 offset:512
	v_lshl_add_u64 v[224:225], v[214:215], 0, s[14:15]
	s_add_i32 s14, s19, 0x8000
	v_lshl_add_u64 v[22:23], s[16:17], 0, v[188:189]
	s_mov_b32 s21, -1
	s_movk_i32 s22, 0x2000
	s_movk_i32 s23, 0x4000
	v_mov_b32_e32 v219, 0
	s_mov_b32 s24, 0
	v_lshl_add_u64 v[226:227], v[216:217], 0, v[22:23]
	v_mov_b32_e32 v17, v16
	v_mov_b32_e32 v22, v16
	v_mov_b32_e32 v23, v16
	s_waitcnt vmcnt(3) lgkmcnt(1)
	v_mfma_f32_32x32x16_bf16 v[64:79], v[18:21], v[172:175], v[48:63]
	s_waitcnt lgkmcnt(0)
	v_mfma_f32_32x32x16_bf16 v[24:39], v[40:43], v[172:175], v[48:63]
	ds_read_b128 v[18:21], v242 offset:2048
	ds_read_b128 v[40:43], v242 offset:2560
	s_waitcnt vmcnt(2) lgkmcnt(1)
	v_mfma_f32_32x32x16_bf16 v[64:79], v[18:21], v[168:171], v[64:79]
	s_waitcnt lgkmcnt(0)
	v_mfma_f32_32x32x16_bf16 v[24:39], v[40:43], v[168:171], v[24:39]
	ds_read_b128 v[18:21], v242 offset:4096
	ds_read_b128 v[40:43], v242 offset:4608
	s_waitcnt vmcnt(1) lgkmcnt(1)
	v_mfma_f32_32x32x16_bf16 v[64:79], v[18:21], v[164:167], v[64:79]
	ds_read_b128 v[44:47], v242 offset:6656
	ds_read_b128 v[18:21], v242 offset:6144
	s_waitcnt lgkmcnt(2)
	v_mfma_f32_32x32x16_bf16 v[24:39], v[40:43], v[164:167], v[24:39]
	v_lshl_add_u64 v[40:41], v[222:223], 0, s[90:91]
	v_lshl_add_u64 v[42:43], v[220:221], 0, s[86:87]
	s_waitcnt vmcnt(0) lgkmcnt(0)
	v_mfma_f32_32x32x16_bf16 v[64:79], v[18:21], v[152:155], v[64:79]
	v_mov_b32_e32 v18, v16
	v_mov_b32_e32 v19, v16
	v_mov_b32_e32 v20, v16
	v_mov_b32_e32 v21, v16
	v_mfma_f32_32x32x16_bf16 v[24:39], v[44:47], v[152:155], v[24:39]
	s_nop 15
	s_nop 7
	s_waitcnt vmcnt(0) lgkmcnt(0)
	s_barrier
	s_mov_b32 s15, m0
	s_mov_b32 m0, s19
	s_nop 0
	global_load_lds_dwordx4 v[40:41], off
	s_mov_b32 m0, s15
	v_mov_b32_e32 v40, v16
	s_mov_b32 s15, m0
	s_mov_b32 m0, s14
	s_nop 0
	global_load_lds_dwordx4 v[42:43], off
	s_mov_b32 m0, s15
	ds_read_b128 v[96:99], v242 offset:8192
	ds_read_b128 v[180:183], v242 offset:8704
	ds_read_b128 v[184:187], v242 offset:10240
	ds_read_b128 v[176:179], v242 offset:10752
	ds_read_b128 v[140:143], v242 offset:12288
	ds_read_b128 v[136:139], v242 offset:12800
	ds_read_b128 v[132:135], v242 offset:14336
	ds_read_b128 v[128:131], v242 offset:14848
	v_exp_f32_e32 v80, v64
	v_exp_f32_e32 v81, v65
	v_exp_f32_e32 v82, v66
	v_exp_f32_e32 v83, v67
	v_exp_f32_e32 v84, v68
	v_exp_f32_e32 v85, v69
	v_exp_f32_e32 v86, v70
	v_exp_f32_e32 v87, v71
	v_exp_f32_e32 v88, v72
	v_exp_f32_e32 v89, v73
	v_exp_f32_e32 v90, v74
	v_exp_f32_e32 v91, v75
	v_exp_f32_e32 v92, v76
	v_exp_f32_e32 v93, v77
	v_exp_f32_e32 v94, v78
	v_exp_f32_e32 v95, v79
	v_exp_f32_e32 v64, v24
	v_exp_f32_e32 v65, v25
	v_exp_f32_e32 v66, v26
	v_exp_f32_e32 v67, v27
	v_exp_f32_e32 v68, v28
	v_exp_f32_e32 v69, v29
	v_exp_f32_e32 v70, v30
	v_exp_f32_e32 v71, v31
	v_exp_f32_e32 v72, v32
	v_exp_f32_e32 v73, v33
	v_exp_f32_e32 v74, v34
	v_exp_f32_e32 v75, v35
	v_exp_f32_e32 v76, v36
	v_exp_f32_e32 v77, v37
	v_exp_f32_e32 v78, v38
	v_exp_f32_e32 v79, v39
	s_waitcnt vmcnt(2) lgkmcnt(0)
	s_barrier
	v_mov_b32_e32 v24, v16
	v_mov_b32_e32 v25, v16
	v_mov_b32_e32 v26, v16
	v_mov_b32_e32 v27, v16
	v_mov_b32_e32 v28, v16
	v_mov_b32_e32 v29, v16
	v_mov_b32_e32 v30, v16
	v_mov_b32_e32 v31, v16
	v_mov_b32_e32 v32, v16
	v_mov_b32_e32 v33, v16
	v_mov_b32_e32 v34, v16
	v_mov_b32_e32 v35, v16
	v_mov_b32_e32 v36, v16
	v_mov_b32_e32 v37, v16
	v_mov_b32_e32 v38, v16
	v_mov_b32_e32 v39, v16
	v_mov_b32_e32 v41, v16
	v_mov_b32_e32 v42, v16
	v_mov_b32_e32 v43, v16
	v_mov_b32_e32 v44, v16
	v_mov_b32_e32 v45, v16
	v_mov_b32_e32 v46, v16
	v_mov_b32_e32 v47, v16

; __global__ void __launch_bounds__(NWAVES * 64, 2) mk_fwd(Args args) {
;     ...
;             __syncthreads();
;         }
;         if (IN(pb + 2)) {
;             PHASE_BEGIN
;             const int h = vcu >> 5, v32 = vcu & 31;
.LBB0_391:
	s_setprio 0
	v_mov_b32_e32 v0, v252
	s_barrier
	s_mov_b32 s37, s81
	v_add_u32_e32 v48, s69, v0
	s_mov_b32 s0, s3
	s_and_b32 s1, s0, 7
	s_cmp_eq_u32 s1, 0
	v_readfirstlane_b32 s58, v48
	s_cbranch_scc0 .LBB0_393
	s_ashr_i32 s1, s37, 31
	s_lshr_b32 s1, s1, 29
	s_add_i32 s1, s37, s1
	s_ashr_i32 s4, s1, 3
	s_and_b32 s1, s1, -8
	s_ashr_i32 s0, s0, 3
	s_sub_i32 s1, s37, s1
	s_mul_i32 s0, s0, s1
	s_add_i32 s37, s0, s4
